# v1 plus padding: attention steady-loop head at 48 mod 64, later phases as v1 mod 64
# speedup vs baseline: 1.0029x; 1.0029x over previous
.LBB0_311:
	s_mov_b32 s37, s36
	s_mov_b32 s4, s33
	s_mov_b32 s1, s42
	v_add_u32_e32 v209, s5, v252
	ds_read_b64_tr_b16 v[216:217], v209 offset:24576
	ds_read_b64_tr_b16 v[218:219], v209 offset:25088
	v_add_f32_e32 v65, v96, v97
	v_add_f32_e32 v65, v98, v65
	v_add_f32_e32 v65, v99, v65
	v_add_f32_e32 v65, v100, v65
	v_add_f32_e32 v65, v101, v65
	v_cvt_pk_bf16_f32 v172, v96, v97
	v_cvt_pk_bf16_f32 v173, v98, v99
	s_waitcnt lgkmcnt(9)
	v_mfma_f32_32x32x16_bf16 v[128:143], v[204:207], v[156:159], v[230:245]
	ds_read_b64_tr_b16 v[204:205], v209 offset:28672
	ds_read_b64_tr_b16 v[206:207], v209 offset:29184
	v_add_f32_e32 v65, v102, v65
	v_add_f32_e32 v65, v103, v65
	v_add_f32_e32 v65, v104, v65
	v_add_f32_e32 v65, v105, v65
	v_cvt_pk_bf16_f32 v174, v100, v101
	v_cvt_pk_bf16_f32 v175, v102, v103
	s_waitcnt lgkmcnt(10)
	v_mfma_f32_32x32x16_bf16 v[112:127], v[200:203], v[156:159], v[230:245]
	ds_read_b64_tr_b16 v[74:75], v209 offset:25600
	ds_read_b64_tr_b16 v[76:77], v209 offset:26112
	v_add_f32_e32 v65, v106, v65
	v_add_f32_e32 v65, v107, v65
	v_add_f32_e32 v65, v108, v65
	v_add_f32_e32 v65, v109, v65
	v_cvt_pk_bf16_f32 v168, v104, v105
	v_cvt_pk_bf16_f32 v169, v106, v107
	s_waitcnt lgkmcnt(11)
	v_mfma_f32_32x32x16_bf16 v[128:143], v[196:199], v[152:155], v[128:143]
	ds_read_b64_tr_b16 v[70:71], v209 offset:29696
	ds_read_b64_tr_b16 v[72:73], v209 offset:30208
	v_add_f32_e32 v65, v110, v65
	v_add_f32_e32 v65, v111, v65
	v_add_f32_e32 v65, v80, v65
	v_add_f32_e32 v65, v81, v65
	v_cvt_pk_bf16_f32 v170, v108, v109
	v_cvt_pk_bf16_f32 v171, v110, v111
	s_waitcnt lgkmcnt(12)
	v_mfma_f32_32x32x16_bf16 v[112:127], v[192:195], v[152:155], v[112:127]
	ds_read_b64_tr_b16 v[66:67], v209 offset:26624
	ds_read_b64_tr_b16 v[68:69], v209 offset:27136
	v_add_f32_e32 v65, v82, v65
	v_add_f32_e32 v65, v83, v65
	v_add_f32_e32 v65, v84, v65
	v_add_f32_e32 v65, v85, v65
	v_cvt_pk_bf16_f32 v164, v80, v81
	v_cvt_pk_bf16_f32 v165, v82, v83
	s_waitcnt lgkmcnt(13)
	v_mfma_f32_32x32x16_bf16 v[128:143], v[188:191], v[148:151], v[128:143]
	ds_read_b64_tr_b16 v[100:101], v209 offset:30720
	ds_read_b64_tr_b16 v[102:103], v209 offset:31232
	v_add_f32_e32 v65, v86, v65
	v_add_f32_e32 v65, v87, v65
	v_add_f32_e32 v65, v88, v65
	v_add_f32_e32 v65, v89, v65
	v_cvt_pk_bf16_f32 v166, v84, v85
	v_cvt_pk_bf16_f32 v167, v86, v87
	s_waitcnt lgkmcnt(14)
	v_mfma_f32_32x32x16_bf16 v[112:127], v[184:187], v[148:151], v[112:127]
	ds_read_b64_tr_b16 v[96:97], v209 offset:27648
	ds_read_b64_tr_b16 v[98:99], v209 offset:28160
	v_add_f32_e32 v65, v90, v65
	v_add_f32_e32 v65, v91, v65
	v_add_f32_e32 v65, v92, v65
	v_add_f32_e32 v65, v93, v65
	v_cvt_pk_bf16_f32 v160, v88, v89
	v_cvt_pk_bf16_f32 v161, v90, v91
	s_waitcnt lgkmcnt(14)
	v_mfma_f32_32x32x16_bf16 v[128:143], v[180:183], v[144:147], v[128:143]
	ds_read_b64_tr_b16 v[86:87], v209 offset:31744
	ds_read_b64_tr_b16 v[88:89], v209 offset:32256
	v_add_f32_e32 v65, v94, v65
	v_add_f32_e32 v65, v95, v65
	v_add_f32_e32 v65, 0, v65
	v_cvt_pk_bf16_f32 v162, v92, v93
	v_cvt_pk_bf16_f32 v163, v94, v95
	v_mfma_f32_32x32x16_bf16 v[112:127], v[176:179], v[144:147], v[112:127]
	v_lshl_add_u64 v[190:191], v[212:213], 0, s[48:49]
	v_lshl_add_u64 v[78:79], v[190:191], 0, s[10:11]
	s_add_i32 s5, s42, s3
	s_mov_b32 s6, m0
	s_mov_b32 m0, s5
	s_nop 0
	global_load_lds_dwordx4 v[78:79], off
	s_mov_b32 m0, s6
	v_lshl_add_u64 v[188:189], v[210:211], 0, s[48:49]
	v_lshl_add_u64 v[78:79], v[188:189], 0, s[12:13]
	s_add_i32 s5, s36, s97
	s_mov_b32 s6, m0
	s_mov_b32 m0, s5
	s_nop 0
	global_load_lds_dwordx4 v[78:79], off
	s_mov_b32 m0, s6
	v_lshl_add_u64 v[78:79], v[188:189], 0, s[14:15]
	s_add_i32 s5, s36, s96
	s_mov_b32 s6, m0
	s_mov_b32 m0, s5
	s_nop 0
	global_load_lds_dwordx4 v[78:79], off
	s_mov_b32 m0, s6
	s_waitcnt lgkmcnt(14)
	v_mfma_f32_32x32x16_bf16 v[32:47], v[172:175], v[216:219], v[32:47]
	v_exp_f32_e32 v128, v128
	v_exp_f32_e32 v129, v129
	ds_read_b64_tr_b16 v[90:91], v209 offset:49152
	ds_read_b64_tr_b16 v[92:93], v209 offset:49664
	s_waitcnt lgkmcnt(14)
	v_mfma_f32_32x32x16_bf16 v[48:63], v[172:175], v[204:207], v[48:63]
	v_exp_f32_e32 v130, v130
	v_exp_f32_e32 v131, v131
	ds_read_b64_tr_b16 v[104:105], v209 offset:53248
	ds_read_b64_tr_b16 v[106:107], v209 offset:53760
	v_add_u32_e32 v94, s37, v250
	ds_read_b128 v[82:85], v94
	ds_read_b128 v[78:81], v94 offset:512
	s_waitcnt lgkmcnt(14)
	v_mfma_f32_32x32x16_bf16 v[32:47], v[168:171], v[74:77], v[32:47]
	v_exp_f32_e32 v132, v132
	v_exp_f32_e32 v133, v133
	ds_read_b64_tr_b16 v[108:109], v209 offset:50176
	ds_read_b64_tr_b16 v[110:111], v209 offset:50688
	ds_read_b128 v[184:187], v94 offset:2048
	ds_read_b128 v[176:179], v94 offset:2560
	v_mfma_f32_32x32x16_bf16 v[48:63], v[168:171], v[70:73], v[48:63]
	v_exp_f32_e32 v134, v134
	v_exp_f32_e32 v135, v135
	ds_read_b64_tr_b16 v[192:193], v209 offset:54272
	ds_read_b64_tr_b16 v[194:195], v209 offset:54784
	ds_read_b128 v[180:183], v94 offset:4096
	ds_read_b128 v[70:73], v94 offset:4608
	s_waitcnt lgkmcnt(14)
	v_mfma_f32_32x32x16_bf16 v[32:47], v[164:167], v[66:69], v[32:47]
	v_exp_f32_e32 v136, v136
	v_exp_f32_e32 v137, v137
	ds_read_b64_tr_b16 v[196:197], v209 offset:51200
	ds_read_b64_tr_b16 v[198:199], v209 offset:51712
	ds_read_b128 v[74:77], v94 offset:6144
	ds_read_b128 v[66:69], v94 offset:6656
	v_mfma_f32_32x32x16_bf16 v[48:63], v[164:167], v[100:103], v[48:63]
	v_exp_f32_e32 v138, v138
	v_exp_f32_e32 v139, v139
	ds_read_b64_tr_b16 v[100:101], v209 offset:55296
	ds_read_b64_tr_b16 v[102:103], v209 offset:55808
	v_mfma_f32_32x32x16_bf16 v[32:47], v[160:163], v[96:99], v[32:47]
	v_exp_f32_e32 v140, v140
	v_exp_f32_e32 v141, v141
	ds_read_b64_tr_b16 v[94:95], v209 offset:52224
	ds_read_b64_tr_b16 v[96:97], v209 offset:52736
	v_mfma_f32_32x32x16_bf16 v[48:63], v[160:163], v[86:89], v[48:63]
	v_exp_f32_e32 v142, v142
	v_exp_f32_e32 v143, v143
	ds_read_b64_tr_b16 v[86:87], v209 offset:56320
	ds_read_b64_tr_b16 v[88:89], v209 offset:56832
	s_waitcnt lgkmcnt(14)
	v_mfma_f32_32x32x16_bf16 v[0:15], v[172:175], v[90:93], v[0:15]
	v_exp_f32_e32 v112, v112
	v_exp_f32_e32 v113, v113
	v_mfma_f32_32x32x16_bf16 v[16:31], v[172:175], v[104:107], v[16:31]
	v_exp_f32_e32 v114, v114
	v_exp_f32_e32 v115, v115
	v_mfma_f32_32x32x16_bf16 v[0:15], v[168:171], v[108:111], v[0:15]
	v_exp_f32_e32 v116, v116
	v_exp_f32_e32 v117, v117
	s_waitcnt lgkmcnt(12)
	v_mfma_f32_32x32x16_bf16 v[16:31], v[168:171], v[192:195], v[16:31]
	v_exp_f32_e32 v118, v118
	v_exp_f32_e32 v119, v119
	s_waitcnt lgkmcnt(8)
	v_mfma_f32_32x32x16_bf16 v[0:15], v[164:167], v[196:199], v[0:15]
	v_exp_f32_e32 v120, v120
	v_exp_f32_e32 v121, v121
	s_waitcnt lgkmcnt(4)
	v_mfma_f32_32x32x16_bf16 v[16:31], v[164:167], v[100:103], v[16:31]
	v_exp_f32_e32 v122, v122
	v_exp_f32_e32 v123, v123
	s_waitcnt lgkmcnt(2)
	v_mfma_f32_32x32x16_bf16 v[0:15], v[160:163], v[94:97], v[0:15]
	v_exp_f32_e32 v124, v124
	v_exp_f32_e32 v125, v125
	s_waitcnt lgkmcnt(0)
	v_mfma_f32_32x32x16_bf16 v[16:31], v[160:163], v[86:89], v[16:31]
	v_exp_f32_e32 v126, v126
	v_exp_f32_e32 v127, v127
	s_waitcnt vmcnt(3) lgkmcnt(0)
	s_barrier
	s_add_i32 s5, s36, 0x2000
	s_cmpk_lg_i32 s36, 0x4000
	s_cselect_b32 s42, s5, 0
	v_add_u32_e32 v209, s1, v252
	ds_read_b64_tr_b16 v[192:193], v209 offset:24576
	ds_read_b64_tr_b16 v[194:195], v209 offset:25088
	v_mfma_f32_32x32x16_bf16 v[96:111], v[82:85], v[156:159], v[230:245]
	v_add_f32_e32 v86, v128, v129
	v_add_f32_e32 v86, v130, v86
	v_add_f32_e32 v86, v131, v86
	v_add_f32_e32 v86, v132, v86
	v_add_f32_e32 v86, v133, v86
	v_cvt_pk_bf16_f32 v172, v128, v129
	v_cvt_pk_bf16_f32 v173, v130, v131
	ds_read_b64_tr_b16 v[196:197], v209 offset:28672
	ds_read_b64_tr_b16 v[198:199], v209 offset:29184
	v_add_f32_e32 v82, v134, v86
	v_add_f32_e32 v82, v135, v82
	v_add_f32_e32 v82, v136, v82
	v_add_f32_e32 v128, v137, v82
	v_mfma_f32_32x32x16_bf16 v[80:95], v[78:81], v[156:159], v[230:245]
	v_cvt_pk_bf16_f32 v174, v132, v133
	v_cvt_pk_bf16_f32 v175, v134, v135
	ds_read_b64_tr_b16 v[216:217], v209 offset:25600
	ds_read_b64_tr_b16 v[218:219], v209 offset:26112
	v_mfma_f32_32x32x16_bf16 v[96:111], v[184:187], v[152:155], v[96:111]
	v_add_f32_e32 v78, v138, v128
	v_add_f32_e32 v78, v139, v78
	v_add_f32_e32 v78, v140, v78
	v_add_f32_e32 v78, v141, v78
	v_cvt_pk_bf16_f32 v168, v136, v137
	v_cvt_pk_bf16_f32 v169, v138, v139
	ds_read_b64_tr_b16 v[136:137], v209 offset:29696
	ds_read_b64_tr_b16 v[138:139], v209 offset:30208
	v_mfma_f32_32x32x16_bf16 v[80:95], v[176:179], v[152:155], v[80:95]
	v_add_f32_e32 v78, v142, v78
	v_add_f32_e32 v78, v143, v78
	v_add_f32_e32 v78, v112, v78
	v_add_f32_e32 v78, v113, v78
	v_cvt_pk_bf16_f32 v170, v140, v141
	v_cvt_pk_bf16_f32 v171, v142, v143
	ds_read_b64_tr_b16 v[132:133], v209 offset:26624
	ds_read_b64_tr_b16 v[134:135], v209 offset:27136
	v_mfma_f32_32x32x16_bf16 v[96:111], v[180:183], v[148:151], v[96:111]
	v_add_f32_e32 v78, v114, v78
	v_add_f32_e32 v78, v115, v78
	v_add_f32_e32 v78, v116, v78
	v_add_f32_e32 v78, v117, v78
	v_cvt_pk_bf16_f32 v164, v112, v113
	v_cvt_pk_bf16_f32 v165, v114, v115
	ds_read_b64_tr_b16 v[128:129], v209 offset:30720
	ds_read_b64_tr_b16 v[130:131], v209 offset:31232
	v_mfma_f32_32x32x16_bf16 v[80:95], v[70:73], v[148:151], v[80:95]
	v_add_f32_e32 v78, v118, v78
	v_add_f32_e32 v78, v119, v78
	v_add_f32_e32 v78, v120, v78
	v_add_f32_e32 v78, v121, v78
	v_cvt_pk_bf16_f32 v166, v116, v117
	v_cvt_pk_bf16_f32 v167, v118, v119
	ds_read_b64_tr_b16 v[112:113], v209 offset:27648
	ds_read_b64_tr_b16 v[114:115], v209 offset:28160
	v_mfma_f32_32x32x16_bf16 v[96:111], v[74:77], v[144:147], v[96:111]
	v_add_f32_e32 v70, v122, v78
	v_add_f32_e32 v70, v123, v70
	v_add_f32_e32 v70, v124, v70
	v_add_f32_e32 v78, v125, v70
	v_cvt_pk_bf16_f32 v160, v120, v121
	v_cvt_pk_bf16_f32 v161, v122, v123
	ds_read_b64_tr_b16 v[70:71], v209 offset:31744
	ds_read_b64_tr_b16 v[72:73], v209 offset:32256
	v_mfma_f32_32x32x16_bf16 v[80:95], v[66:69], v[144:147], v[80:95]
	v_add_f32_e32 v74, v126, v78
	v_add_f32_e32 v74, v127, v74
	v_add_f32_e32 v74, 0, v74
	v_cvt_pk_bf16_f32 v162, v124, v125
	v_cvt_pk_bf16_f32 v163, v126, v127
	v_lshl_add_u64 v[66:67], v[190:191], 0, s[16:17]
	s_add_i32 s1, s36, s3
	s_mov_b32 s5, m0
	s_mov_b32 m0, s1
	s_nop 0
	global_load_lds_dwordx4 v[66:67], off
	s_mov_b32 m0, s5
	v_lshl_add_u64 v[66:67], v[188:189], 0, s[18:19]
	s_add_i32 s1, s42, s97
	s_mov_b32 s5, m0
	s_mov_b32 m0, s1
	s_nop 0
	global_load_lds_dwordx4 v[66:67], off
	s_mov_b32 m0, s5
	v_lshl_add_u64 v[66:67], v[188:189], 0, s[20:21]
	s_add_i32 s1, s42, s96
	s_mov_b32 s5, m0
	s_mov_b32 m0, s1
	s_nop 0
	global_load_lds_dwordx4 v[66:67], off
	s_mov_b32 m0, s5
	s_waitcnt lgkmcnt(14)
; #define WAIT_BAR(N) asm volatile("s_waitcnt vmcnt(" #N ") lgkmcnt(0)\n\ts_barrier":::"memory")
;   #define RESC() do{ if(resc){ asm volatile("s_waitcnt lgkmcnt(0)":::"memory"); \
;       _Pragma("unroll") for(int d_=0;d_<2;++d_) _Pragma("unroll") for(int r=0;r<16;++r){const float f_=wsf[crow(r,hi)];o[d_][r]*=f_;o2[d_][r]*=f_;} } }while(0)
;   #define ROT() do{sl_prev=sl_cur;sl_cur=sl_next;sl_next=(sl_next==(NSLOT-1)*SLOTB)?0:sl_next+SLOTB;}while(0)
; template<int THRL> __device__ __forceinline__ void attn_unit(int b,int h,int qb,unsigned char*wsb,char*shm,float kmax,const int CMB,float lam){
;     ...
;   int t=1;
;     ...
;   for(;t+5<NT;t+=2){
;     STEP(pB0,pB1,pA0,pA1,t,true,true,true);     WAIT_BAR(3); RESC(); ROT();
;     STEP(pA0,pA1,pB0,pB1,t+1,true,true,true);   WAIT_BAR(3); RESC(); ROT();
;   }
	v_mfma_f32_32x32x16_bf16 v[32:47], v[172:175], v[192:195], v[32:47]
	v_exp_f32_e32 v96, v96
	v_exp_f32_e32 v97, v97
	ds_read_b64_tr_b16 v[66:67], v209 offset:49152
	ds_read_b64_tr_b16 v[68:69], v209 offset:49664
	s_waitcnt lgkmcnt(14)
	v_mfma_f32_32x32x16_bf16 v[48:63], v[172:175], v[196:199], v[48:63]
	v_exp_f32_e32 v98, v98
	v_exp_f32_e32 v99, v99
	ds_read_b64_tr_b16 v[76:77], v209 offset:53248
	ds_read_b64_tr_b16 v[78:79], v209 offset:53760
	v_add_u32_e32 v75, s42, v250
	ds_read_b128 v[204:207], v75
	ds_read_b128 v[200:203], v75 offset:512
	s_waitcnt lgkmcnt(14)
	v_mfma_f32_32x32x16_bf16 v[32:47], v[168:171], v[216:219], v[32:47]
	v_exp_f32_e32 v100, v100
	v_exp_f32_e32 v101, v101
	ds_read_b64_tr_b16 v[116:117], v209 offset:50176
	ds_read_b64_tr_b16 v[118:119], v209 offset:50688
	ds_read_b128 v[196:199], v75 offset:2048
	ds_read_b128 v[192:195], v75 offset:2560
	v_mfma_f32_32x32x16_bf16 v[48:63], v[168:171], v[136:139], v[48:63]
	v_exp_f32_e32 v102, v102
	v_exp_f32_e32 v103, v103
	ds_read_b64_tr_b16 v[120:121], v209 offset:54272
	ds_read_b64_tr_b16 v[122:123], v209 offset:54784
	ds_read_b128 v[188:191], v75 offset:4096
	ds_read_b128 v[184:187], v75 offset:4608
	s_waitcnt lgkmcnt(14)
	v_mfma_f32_32x32x16_bf16 v[32:47], v[164:167], v[132:135], v[32:47]
	v_exp_f32_e32 v104, v104
	v_exp_f32_e32 v105, v105
	ds_read_b64_tr_b16 v[124:125], v209 offset:51200
	ds_read_b64_tr_b16 v[126:127], v209 offset:51712
	ds_read_b128 v[180:183], v75 offset:6144
	ds_read_b128 v[176:179], v75 offset:6656
	v_mfma_f32_32x32x16_bf16 v[48:63], v[164:167], v[128:131], v[48:63]
	v_exp_f32_e32 v106, v106
	v_exp_f32_e32 v107, v107
	ds_read_b64_tr_b16 v[128:129], v209 offset:55296
	ds_read_b64_tr_b16 v[130:131], v209 offset:55808
	v_mfma_f32_32x32x16_bf16 v[32:47], v[160:163], v[112:115], v[32:47]
	v_exp_f32_e32 v108, v108
	v_exp_f32_e32 v109, v109
	ds_read_b64_tr_b16 v[112:113], v209 offset:52224
	ds_read_b64_tr_b16 v[114:115], v209 offset:52736
	v_mfma_f32_32x32x16_bf16 v[48:63], v[160:163], v[70:73], v[48:63]
	v_exp_f32_e32 v110, v110
	v_exp_f32_e32 v111, v111
	ds_read_b64_tr_b16 v[70:71], v209 offset:56320
	ds_read_b64_tr_b16 v[72:73], v209 offset:56832
	s_waitcnt lgkmcnt(14)
	v_mfma_f32_32x32x16_bf16 v[0:15], v[172:175], v[66:69], v[0:15]
	v_exp_f32_e32 v80, v80
	v_exp_f32_e32 v81, v81
	v_mfma_f32_32x32x16_bf16 v[16:31], v[172:175], v[76:79], v[16:31]
	v_exp_f32_e32 v82, v82
	v_exp_f32_e32 v83, v83
	v_mfma_f32_32x32x16_bf16 v[0:15], v[168:171], v[116:119], v[0:15]
	v_exp_f32_e32 v84, v84
	v_exp_f32_e32 v85, v85
	s_waitcnt lgkmcnt(12)
	v_mfma_f32_32x32x16_bf16 v[16:31], v[168:171], v[120:123], v[16:31]
	v_exp_f32_e32 v86, v86
	v_exp_f32_e32 v87, v87
	s_waitcnt lgkmcnt(8)
	v_mfma_f32_32x32x16_bf16 v[0:15], v[164:167], v[124:127], v[0:15]
	v_exp_f32_e32 v88, v88
	v_exp_f32_e32 v89, v89
	s_waitcnt lgkmcnt(4)
	v_mfma_f32_32x32x16_bf16 v[16:31], v[164:167], v[128:131], v[16:31]
	v_exp_f32_e32 v90, v90
	v_exp_f32_e32 v91, v91
	s_waitcnt lgkmcnt(2)
	v_mfma_f32_32x32x16_bf16 v[0:15], v[160:163], v[112:115], v[0:15]
	v_exp_f32_e32 v92, v92
	v_exp_f32_e32 v93, v93
	s_waitcnt lgkmcnt(0)
	v_mfma_f32_32x32x16_bf16 v[16:31], v[160:163], v[70:73], v[16:31]
	v_exp_f32_e32 v94, v94
	v_exp_f32_e32 v95, v95
	s_add_i32 s1, s42, 0x2000
	s_waitcnt vmcnt(3) lgkmcnt(0)
	s_barrier
	s_cmpk_lg_i32 s42, 0x4000
	v_add_f32_e32 v64, v64, v65
	s_mov_b32 s5, s36
	s_cselect_b32 s36, s1, 0
	s_add_i32 s33, s33, 2
	v_lshl_add_u64 v[210:211], v[210:211], 0, s[22:23]
	v_lshl_add_u64 v[212:213], v[212:213], 0, s[22:23]
	s_cmp_ge_u32 s33, s89
	v_add_f32_e32 v64, v64, v74
	s_cbranch_scc0 .LBB0_311
	ds_read_b32 v230, v246
	ds_read_b32 v231, v246 offset:2048
	ds_read_b32 v232, v246 offset:4096
	ds_read_b32 v233, v246 offset:6144
	ds_read_b32 v234, v246 offset:8192
	ds_read_b32 v235, v246 offset:10240
	ds_read_b32 v236, v246 offset:12288
	ds_read_b32 v237, v246 offset:14336
	ds_read_b32 v238, v246 offset:16384
	ds_read_b32 v239, v246 offset:18432
	ds_read_b32 v240, v246 offset:20480
	ds_read_b32 v241, v246 offset:22528
	ds_read_b32 v242, v246 offset:24576
	ds_read_b32 v243, v246 offset:26624
	ds_read_b32 v244, v246 offset:28672
	ds_read_b32 v245, v246 offset:30720
	ds_read_b32 v246, v246 offset:32768
	s_waitcnt lgkmcnt(0)
	s_nop 0
	s_nop 0
	s_nop 0
	s_nop 0
	s_nop 0
	s_nop 0
	s_nop 0
	s_nop 0
	s_nop 0
	s_nop 0
	s_nop 0
	s_nop 0
	s_nop 0
	s_nop 0
	s_add_i32 s6, s4, -3
	s_branch .LBB0_314
